# c22 + pass C: next queue atomic issued by wave 0 before the token loop (private register), so the unit-top fetch only collects it
# speedup vs baseline: 1.0017x; 1.0017x over previous
.LBB0_1110:
	v_mov_b32_e32 v39, 0x25200
	s_waitcnt lgkmcnt(0)
	s_barrier
	ds_read_b32 v50, v39
	s_movk_i32 s0, 0x10f
	s_mul_i32 s33, s80, 0x104
	s_waitcnt lgkmcnt(0)
	v_cmp_lt_i32_e32 vcc, s0, v50
	v_readfirstlane_b32 s30, v50
	s_cbranch_vccnz .LBB0_1234
	v_readlane_b32 s0, v254, 34
	s_or_b32 s17, s54, 0x800
	s_and_b32 s46, s0, 0xffffffc0
	s_add_u32 s20, s78, 0x10c9000
	s_addc_u32 s21, s79, 0
	s_add_u32 s47, s78, 0x1e467000
	s_addc_u32 s48, s79, 0
	s_add_u32 s49, s78, 0x18731000
	s_addc_u32 s50, s79, 0
	s_add_u32 s51, s78, 0x14731000
	s_addc_u32 s52, s79, 0
	s_add_u32 s53, s78, 0x18931000
	v_readlane_b32 s0, v254, 2
	s_addc_u32 s58, s79, 0
	v_readlane_b32 s4, v254, 6
	v_readlane_b32 s5, v254, 7
	s_add_u32 s22, s4, 0x1000
	s_addc_u32 s23, s5, 0
	s_add_u32 s24, s4, 0x1900
	s_addc_u32 s25, s5, 0
	s_add_u32 s26, s4, 0x1a00
	s_addc_u32 s27, s5, 0
	s_lshl_b32 s0, s80, 3
	s_and_b32 s59, s0, 0x1ffffff0
	s_add_u32 s60, s78, 0x1cb31000
	s_mov_b64 s[34:35], s[90:91]
	s_addc_u32 s61, s79, 0
	s_waitcnt vmcnt(48)
	v_cvt_pk_bf16_f32 v0, v0, v1
	s_waitcnt vmcnt(41)
	v_cvt_pk_bf16_f32 v1, v11, v2
	s_waitcnt vmcnt(39)
	v_cvt_pk_bf16_f32 v2, v12, v13
	s_waitcnt vmcnt(18)
	v_cvt_pk_bf16_f32 v13, v14, v31
	s_waitcnt vmcnt(17)
	v_cvt_pk_bf16_f32 v14, v16, v38
	s_waitcnt vmcnt(16)
	v_cvt_pk_bf16_f32 v16, v24, v32
	v_readlane_b32 s2, v254, 4
	v_readlane_b32 s3, v254, 5
	s_add_u32 s28, s78, 0xe671400
	v_cndmask_b32_e64 v24, 0, 1, s[34:35]
	s_movk_i32 s34, 0xf2c0
	s_movk_i32 s40, 0xc000
	v_cvt_pk_bf16_f32 v3, v3, v22
	v_cvt_pk_bf16_f32 v4, v7, v4
	v_cvt_pk_bf16_f32 v5, v6, v5
	v_cvt_pk_bf16_f32 v6, v17, v10
	v_cvt_pk_bf16_f32 v7, v23, v21
	v_cvt_pk_bf16_f32 v8, v8, v20
	v_cvt_pk_bf16_f32 v9, v9, v27
	v_cvt_pk_bf16_f32 v10, v28, v19
	v_cvt_pk_bf16_f32 v11, v29, v30
	v_cvt_pk_bf16_f32 v12, v18, v15
	v_cvt_pk_bf16_f32 v15, v26, v25
	s_waitcnt vmcnt(9)
	v_cvt_pk_bf16_f32 v17, v44, v45
	s_waitcnt vmcnt(8)
	v_cvt_pk_bf16_f32 v18, v46, v34
	s_waitcnt vmcnt(6)
	v_cvt_pk_bf16_f32 v19, v47, v48
	v_cvt_pk_bf16_f32 v20, v40, v33
	s_waitcnt vmcnt(3)
	v_cvt_pk_bf16_f32 v21, v43, v42
	v_cvt_pk_bf16_f32 v22, v36, v35
	s_waitcnt vmcnt(2)
	v_cvt_pk_bf16_f32 v23, v41, v49
	s_addc_u32 s29, s79, 0
	s_movk_i32 s62, 0x104
	v_cmp_ne_u32_e64 s[2:3], 1, v24
	s_mov_b32 s31, 0
	v_mov_b32_e32 v55, 0
	s_movk_i32 s63, 0xd40
	s_mov_b32 s35, -1
	s_movk_i32 s64, 0x7f
	s_mov_b32 s41, -1
	s_movk_i32 s65, 0x190
	v_mov_b32_e32 v51, 0x3a27c5ac
	s_mov_b32 s66, 0x800000
	v_mov_b32_e32 v64, 0x14500
	v_mov_b32_e32 v65, 0xb80
	v_mov_b32_e32 v66, 0x18600
	v_readlane_b32 s1, v254, 3
	v_readlane_b32 s6, v254, 8
	v_readlane_b32 s7, v254, 9
	v_readlane_b32 s8, v254, 10
	v_readlane_b32 s9, v254, 11
	v_readlane_b32 s10, v254, 12
	v_readlane_b32 s11, v254, 13
	v_readlane_b32 s12, v254, 14
	v_readlane_b32 s13, v254, 15
	v_readlane_b32 s14, v254, 16
	v_readlane_b32 s15, v254, 17
	s_mov_b32 s32, 0
	s_branch .LBB0_1113

.LBB0_1166:
	s_or_b64 exec, exec, s[0:1]
	v_lshlrev_b32_e32 v58, 2, v79
	v_lshlrev_b32_e32 v54, 2, v75
	global_load_dwordx2 v[60:61], v58, s[22:23]
	s_nop 0
	global_load_dwordx2 v[58:59], v54, s[24:25]
	v_ashrrev_i32_e32 v79, 3, v67
	v_and_b32_e32 v56, 56, v56
	v_mul_lo_u32 v79, v79, s62
	v_lshl_add_u32 v56, v56, 2, v79
	s_mov_b64 s[82:83], vcc
	s_and_b64 vcc, exec, s[2:3]
	s_barrier
	s_cbranch_vccnz .Lpc4a_q3
	s_cmp_eq_u32 s32, 0
	s_cbranch_scc1 .Lpc4a_orig
	s_waitcnt vmcnt(0)
	v_readfirstlane_b32 s94, v108
	s_nop 1
	v_mov_b32_e32 v102, s94
	ds_write_b32 v39, v102
	s_branch .Lpc4a_q3
.Lpc4a_orig:
	v_mbcnt_lo_u32_b32 v102, -1, 0
	v_mbcnt_hi_u32_b32 v102, -1, v102
	s_nop 0
	v_cmp_eq_u32_e32 vcc, 0, v102
	s_and_saveexec_b64 s[92:93], vcc
	s_cbranch_execz .Lpc4a_q2
	s_mov_b64 s[96:97], exec
	v_mbcnt_lo_u32_b32 v102, s96, 0
	v_mbcnt_hi_u32_b32 v102, s97, v102
	v_cmp_eq_u32_e32 vcc, 0, v102
	s_and_saveexec_b64 s[94:95], vcc
	s_cbranch_execz .Lpc4a_q1
	s_bcnt1_i32_b64 s96, s[96:97]
	v_mov_b32_e32 v103, s96
	global_atomic_add v103, v55, v103, s[18:19] offset:256 sc0

.Lpct_a:
	s_and_b64 s[94:95], exec, s[2:3]
	s_cbranch_scc1 .Lpcq_a
	v_mbcnt_lo_u32_b32 v107, -1, 0
	v_mbcnt_hi_u32_b32 v107, -1, v107
	v_cmp_eq_u32_e64 s[94:95], 0, v107
	s_and_saveexec_b64 s[92:93], s[94:95]
	v_mov_b32_e32 v108, 1
	global_atomic_add v108, v55, v108, s[18:19] offset:256 sc0
	s_or_b64 exec, exec, s[92:93]
.Lpcq_a:
	s_mov_b32 s32, 1
	s_branch .LBB0_1229

.LBB0_1296:
	v_mov_b32_e32 v41, 0x25200
	s_waitcnt lgkmcnt(0)
	s_barrier
	ds_read_b32 v50, v41
	s_movk_i32 s17, 0xff
	s_waitcnt lgkmcnt(0)
	v_cmp_lt_i32_e32 vcc, s17, v50
	v_readfirstlane_b32 s42, v50
	s_cbranch_vccnz .LBB0_1401
	v_readlane_b32 s0, v254, 34
	s_and_b32 s46, s0, 0xffffffc0
	s_add_u32 s20, s78, 0x10c9000
	s_addc_u32 s21, s79, 0
	s_add_u32 s47, s78, 0x1e467000
	s_addc_u32 s48, s79, 0
	s_add_u32 s49, s78, 0x18731000
	s_addc_u32 s50, s79, 0
	s_add_u32 s51, s78, 0x14731000
	s_addc_u32 s52, s79, 0
	s_add_u32 s53, s78, 0x18931000
	v_readlane_b32 s0, v254, 2
	s_addc_u32 s58, s79, 0
	v_readlane_b32 s4, v254, 6
	v_readlane_b32 s5, v254, 7
	s_add_u32 s22, s4, 0x1000
	s_addc_u32 s23, s5, 0
	s_add_u32 s24, s4, 0x1900
	s_addc_u32 s25, s5, 0
	s_add_u32 s26, s4, 0x1a00
	s_addc_u32 s27, s5, 0
	s_lshl_b32 s0, s80, 3
	s_and_b32 s59, s0, 0x1ffffff0
	v_readlane_b32 s1, v254, 3
	s_add_u32 s0, s78, s57
	s_addc_u32 s1, s79, 0
	s_add_u32 s57, s0, 0x1cb31000
	s_addc_u32 s60, s1, 0
	s_add_u32 s30, s78, 0xe671400
	s_movk_i32 s34, 0xf2c0
	s_movk_i32 s40, 0xc000
	s_waitcnt vmcnt(48)
	v_cvt_pk_bf16_f32 v0, v0, v1
	s_waitcnt vmcnt(41)
	v_cvt_pk_bf16_f32 v1, v11, v2
	s_waitcnt vmcnt(39)
	v_cvt_pk_bf16_f32 v2, v12, v13
	s_waitcnt vmcnt(33)
	v_cvt_pk_bf16_f32 v3, v3, v22
	v_cvt_pk_bf16_f32 v4, v7, v4
	v_cvt_pk_bf16_f32 v5, v6, v5
	v_cvt_pk_bf16_f32 v6, v17, v10
	s_waitcnt vmcnt(26)
	v_cvt_pk_bf16_f32 v7, v23, v21
	v_cvt_pk_bf16_f32 v8, v8, v20
	s_waitcnt vmcnt(25)
	v_cvt_pk_bf16_f32 v9, v9, v27
	s_waitcnt vmcnt(24)
	v_cvt_pk_bf16_f32 v10, v28, v19
	s_waitcnt vmcnt(22)
	v_cvt_pk_bf16_f32 v11, v29, v30
	v_cvt_pk_bf16_f32 v12, v18, v15
	s_waitcnt vmcnt(18)
	v_cvt_pk_bf16_f32 v13, v14, v31
	s_waitcnt vmcnt(17)
	v_cvt_pk_bf16_f32 v14, v16, v38
	v_cvt_pk_bf16_f32 v15, v26, v25
	s_waitcnt vmcnt(16)
	v_cvt_pk_bf16_f32 v16, v24, v32
	s_waitcnt vmcnt(9)
	v_cvt_pk_bf16_f32 v17, v44, v45
	s_waitcnt vmcnt(8)
	v_cvt_pk_bf16_f32 v18, v46, v34
	s_waitcnt vmcnt(6)
	v_cvt_pk_bf16_f32 v19, v47, v48
	v_cvt_pk_bf16_f32 v20, v39, v33
	s_waitcnt vmcnt(3)
	v_cvt_pk_bf16_f32 v21, v43, v42
	v_cvt_pk_bf16_f32 v22, v37, v36
	s_waitcnt vmcnt(2)
	v_cvt_pk_bf16_f32 v23, v40, v49
	s_mov_b32 s29, 0
	s_addc_u32 s31, s79, 0
	s_or_b32 s61, s54, 0x400
	s_movk_i32 s62, 0x104
	v_mov_b32_e32 v55, 0
	s_movk_i32 s63, 0xd40
	s_mov_b32 s35, -1
	s_movk_i32 s64, 0x64
	s_movk_i32 s65, 0x1040
	s_movk_i32 s66, 0x2080
	s_movk_i32 s67, 0x30c0
	s_movk_i32 s68, 0x7f
	s_mov_b32 s41, -1
	s_movk_i32 s69, 0x190
	v_mov_b32_e32 v51, 0x3a27c5ac
	s_mov_b32 s70, 0x800000
	v_mov_b32_e32 v64, 0x14500
	v_mov_b32_e32 v65, 0xb80
	v_mov_b32_e32 v66, 0x18600
	v_readlane_b32 s2, v254, 4
	v_readlane_b32 s3, v254, 5
	v_readlane_b32 s6, v254, 8
	v_readlane_b32 s7, v254, 9
	v_readlane_b32 s8, v254, 10
	v_readlane_b32 s9, v254, 11
	v_readlane_b32 s10, v254, 12
	v_readlane_b32 s11, v254, 13
	v_readlane_b32 s12, v254, 14
	v_readlane_b32 s13, v254, 15
	v_readlane_b32 s14, v254, 16
	v_readlane_b32 s15, v254, 17
	s_mov_b32 s32, 0
	s_branch .LBB0_1299

.LBB0_1333:
	s_or_b64 exec, exec, s[0:1]
	v_lshlrev_b32_e32 v56, 2, v79
	v_lshlrev_b32_e32 v54, 2, v77
	global_load_dwordx2 v[60:61], v56, s[22:23]
	s_nop 0
	global_load_dwordx2 v[56:57], v54, s[24:25]
	v_ashrrev_i32_e32 v79, 3, v67
	v_and_b32_e32 v58, 56, v58
	v_mul_lo_u32 v79, v79, s62
	v_lshl_add_u32 v58, v58, 2, v79
	s_mov_b64 s[82:83], vcc
	s_and_b64 vcc, exec, s[88:89]
	s_barrier
	s_cbranch_vccnz .Lpc4b_q3
	s_cmp_eq_u32 s32, 0
	s_cbranch_scc1 .Lpc4b_orig
	s_waitcnt vmcnt(0)
	v_readfirstlane_b32 s94, v108
	s_nop 1
	v_mov_b32_e32 v102, s94
	ds_write_b32 v41, v102
	s_branch .Lpc4b_q3
.Lpc4b_orig:
	v_mbcnt_lo_u32_b32 v102, -1, 0
	v_mbcnt_hi_u32_b32 v102, -1, v102
	s_nop 0
	v_cmp_eq_u32_e32 vcc, 0, v102
	s_and_saveexec_b64 s[92:93], vcc
	s_cbranch_execz .Lpc4b_q2
	s_mov_b64 s[96:97], exec
	v_mbcnt_lo_u32_b32 v102, s96, 0
	v_mbcnt_hi_u32_b32 v102, s97, v102
	v_cmp_eq_u32_e32 vcc, 0, v102
	s_and_saveexec_b64 s[94:95], vcc
	s_cbranch_execz .Lpc4b_q1
	s_bcnt1_i32_b64 s96, s[96:97]
	v_mov_b32_e32 v103, s96
	global_atomic_add v103, v55, v103, s[18:19] offset:320 sc0

.Lpct_b:
	s_and_b64 s[94:95], exec, s[88:89]
	s_cbranch_scc1 .Lpcq_b
	v_mbcnt_lo_u32_b32 v107, -1, 0
	v_mbcnt_hi_u32_b32 v107, -1, v107
	v_cmp_eq_u32_e64 s[94:95], 0, v107
	s_and_saveexec_b64 s[92:93], s[94:95]
	v_mov_b32_e32 v108, 1
	global_atomic_add v108, v55, v108, s[18:19] offset:320 sc0
	s_or_b64 exec, exec, s[92:93]
